# Hyena filter GEMM moved out of the hyin phase into the idle tail of the preceding w13 phase (WGs 192-255 have only 2 of 3 tile rounds)
# speedup vs baseline: 1.0244x; 1.0138x over previous
.LBB0_6:
	v_readlane_b32 s20, v252, 0
	v_readlane_b32 s21, v252, 1
	s_add_u32 s0, s20, 0x208
	s_load_dwordx16 s[56:71], s[20:21], 0x130
	s_addc_u32 s1, s21, 0
	v_writelane_b32 v252, s0, 10
	s_load_dwordx16 s[36:51], s[20:21], 0x170
	v_lshrrev_b32_e32 v1, 20, v0
	v_writelane_b32 v252, s1, 11
	s_add_u32 s0, s20, 0x200
	s_addc_u32 s1, s21, 0
	v_writelane_b32 v252, s0, 12
	s_waitcnt lgkmcnt(0)
	s_cmp_lg_u64 s[70:71], 0
	s_cselect_b64 s[4:5], -1, 0
	v_writelane_b32 v252, s1, 13
	v_writelane_b32 v252, s4, 14
	s_load_dword s1, s[20:21], 0x2a0
	s_mul_i32 s0, s35, s34
	v_writelane_b32 v252, s5, 15
	s_add_u32 s4, s36, 0x3000000
	s_addc_u32 s5, s37, 0
	v_writelane_b32 v252, s4, 16
	s_waitcnt lgkmcnt(0)
	s_mul_i32 s90, s0, s1
	v_lshrrev_b32_e32 v0, 10, v0
	v_writelane_b32 v252, s5, 17
	s_add_u32 s4, s36, 0x2000000
	s_addc_u32 s5, s37, 0
	v_writelane_b32 v252, s4, 18
	v_or_b32_e32 v0, v0, v1
	v_mov_b32_e32 v1, 0
	v_writelane_b32 v252, s5, 19
	v_mbcnt_lo_u32_b32 v2, -1, 0
	v_readlane_b32 s4, v252, 6
	v_readlane_b32 s5, v252, 7
	s_add_u32 s0, s4, 0x200
	s_addc_u32 s1, s5, 0
	v_writelane_b32 v252, s0, 20
	v_mov_b32_e32 v197, 0x358637bd
	v_mov_b32_e32 v200, 0x3000
	v_writelane_b32 v252, s1, 21
	s_add_u32 s0, s4, 0x1000
	s_addc_u32 s1, s5, 0
	v_writelane_b32 v252, s0, 22
	v_mov_b32_e32 v201, 0x6000
	v_mov_b32_e32 v202, 0x3a27c5ac
	v_writelane_b32 v252, s1, 23
	s_add_u32 s0, s4, 0x1100
	s_addc_u32 s1, s5, 0
	v_writelane_b32 v252, s0, 24
	v_mov_b32_e32 v204, 0x260
	v_mov_b32_e32 v206, 0x3c0881c4
	v_writelane_b32 v252, s1, 25
	s_add_u32 s0, s4, 0x1200
	s_addc_u32 s1, s5, 0
	v_writelane_b32 v252, s0, 26
	v_mov_b32_e32 v207, 0xbab64f3b
	v_mbcnt_hi_u32_b32 v209, -1, v2
	v_writelane_b32 v252, s1, 27
	s_add_u32 s0, s4, 0x1300
	s_addc_u32 s1, s5, 0
	v_writelane_b32 v252, s0, 28
	s_cmp_eq_u32 s3, 15
	v_mov_b32_e32 v210, v1
	v_writelane_b32 v252, s1, 29
	s_cselect_b64 s[0:1], -1, 0
	v_writelane_b32 v252, s0, 30
	s_cmp_eq_u32 s3, 14
	v_mov_b32_e32 v211, v1
	v_writelane_b32 v252, s1, 31
	s_cselect_b64 s[0:1], -1, 0
	v_writelane_b32 v252, s0, 32
	s_cmp_eq_u32 s3, 13
	v_mov_b32_e32 v212, v1
	v_writelane_b32 v252, s1, 33
	s_cselect_b64 s[0:1], -1, 0
	v_writelane_b32 v252, s0, 34
	s_cmp_eq_u32 s3, 12
	v_mov_b32_e32 v213, v1
	v_writelane_b32 v252, s1, 35
	s_cselect_b64 s[0:1], -1, 0
	v_writelane_b32 v252, s0, 36
	s_cmp_eq_u32 s3, 11
	v_mov_b32_e32 v208, 0xfffffd80
	v_writelane_b32 v252, s1, 37
	s_cselect_b64 s[0:1], -1, 0
	v_writelane_b32 v252, s0, 38
	s_cmp_eq_u32 s3, 10
	v_mov_b32_e32 v203, 0xfffffce0
	v_writelane_b32 v252, s1, 39
	s_cselect_b64 s[0:1], -1, 0
	v_writelane_b32 v252, s0, 40
	s_cmp_eq_u32 s3, 9
	v_mov_b32_e32 v223, 0xfffffc40
	v_writelane_b32 v252, s1, 41
	s_cselect_b64 s[0:1], -1, 0
	v_writelane_b32 v252, s0, 42
	s_cmp_eq_u32 s3, 8
	v_mov_b32_e32 v229, 0xfffffb50
	v_writelane_b32 v252, s1, 43
	s_cselect_b64 s[0:1], -1, 0
	v_writelane_b32 v252, s0, 44
	s_cmp_eq_u32 s3, 7
	v_mov_b32_e32 v230, 0xfffffb00
	v_writelane_b32 v252, s1, 45
	s_cselect_b64 s[0:1], -1, 0
	v_writelane_b32 v252, s0, 46
	s_cmp_eq_u32 s3, 6
	v_mov_b32_e32 v205, 0xfffff9c0
	v_writelane_b32 v252, s1, 47
	s_cselect_b64 s[0:1], -1, 0
	v_writelane_b32 v252, s0, 48
	s_cmp_eq_u32 s3, 5
	v_mov_b32_e32 v198, 0x7f800000
	v_writelane_b32 v252, s1, 49
	s_cselect_b64 s[0:1], -1, 0
	v_writelane_b32 v252, s0, 50
	s_cmp_eq_u32 s3, 4
	v_mov_b32_e32 v199, 0x100
	v_writelane_b32 v252, s1, 51
	s_cselect_b64 s[0:1], -1, 0
	v_writelane_b32 v252, s0, 52
	s_cmp_eq_u32 s3, 3
	v_mov_b32_e32 v250, 0x41b17218
	v_writelane_b32 v252, s1, 53
	s_cselect_b64 s[0:1], -1, 0
	v_writelane_b32 v252, s0, 54
	s_cmp_eq_u32 s3, 2
	v_mov_b32_e32 v251, 0x1c00
	v_writelane_b32 v252, s1, 55
	s_cselect_b64 s[0:1], -1, 0
	v_writelane_b32 v252, s0, 56
	s_cmp_eq_u32 s3, 1
	v_mov_b32_e32 v222, 0x800
	v_writelane_b32 v252, s1, 57
	s_cselect_b64 s[0:1], -1, 0
	v_writelane_b32 v252, s0, 58
	s_cmp_eq_u32 s3, 0
	v_not_b32_e32 v224, 63
	v_writelane_b32 v252, s1, 59
	s_cselect_b64 s[0:1], -1, 0
	v_writelane_b32 v252, s0, 60
	v_not_b32_e32 v225, 31
	v_mov_b32_e32 v226, 0xffc00000
	v_writelane_b32 v252, s1, 61
	s_lshl_b32 s0, s3, 8
	s_add_u32 s0, s4, s0
	s_addc_u32 s1, s5, 0
	s_add_u32 s6, s0, 0x1400
	s_addc_u32 s7, s1, 0
	s_add_u32 s0, s0, 0x2400
	s_addc_u32 s1, s1, 0
	v_writelane_b32 v253, s0, 0
	v_writelane_b32 v252, s6, 62
	v_mov_b32_e32 v227, 0x7fc00000
	v_writelane_b32 v253, s1, 1
	s_add_u32 s0, s4, 0x3400
	s_addc_u32 s1, s5, 0
	v_writelane_b32 v253, s0, 2
	v_writelane_b32 v252, s7, 63
	v_mov_b32_e32 v228, 0x900
	v_writelane_b32 v253, s1, 3
	s_add_u32 s0, s4, 0x3500
	s_addc_u32 s1, s5, 0
	v_writelane_b32 v253, s0, 4
	s_mov_b32 s3, 0x2aaaaaab
	s_mov_b32 s96, 0x3c000
	v_writelane_b32 v253, s1, 5
	s_movk_i32 s0, 0x3ff
	v_and_or_b32 v0, v0, s0, v196
	s_load_dwordx2 s[0:1], s[20:21], 0x288
	s_load_dwordx4 s[4:7], s[20:21], 0x278
	s_movk_i32 s93, 0x1f8
	s_mov_b32 s35, 0x18000
	s_mov_b32 s97, 0x54000
	s_mov_b32 s31, 0
	s_waitcnt lgkmcnt(0)
	s_add_u32 s8, s6, 0x80000
	v_writelane_b32 v253, s4, 6
	s_addc_u32 s9, s7, 0
	s_nop 0
	v_writelane_b32 v253, s5, 7
	v_writelane_b32 v253, s6, 8
	v_writelane_b32 v253, s7, 9
	v_writelane_b32 v253, s8, 10
	s_add_u32 s4, s62, 0x100000
	s_addc_u32 s5, s63, 0
	v_writelane_b32 v253, s9, 11
	v_writelane_b32 v253, s4, 12
	s_nop 1
	v_writelane_b32 v253, s5, 13
	s_add_u32 s4, s42, 8
	v_writelane_b32 v253, s36, 14
	s_addc_u32 s5, s43, 0
	s_nop 0
	v_writelane_b32 v253, s37, 15
	v_writelane_b32 v253, s38, 16
	v_writelane_b32 v253, s39, 17
	v_writelane_b32 v253, s40, 18
	v_writelane_b32 v253, s41, 19
	v_writelane_b32 v253, s42, 20
	v_writelane_b32 v253, s43, 21
	v_writelane_b32 v253, s44, 22
	v_writelane_b32 v253, s45, 23
	v_writelane_b32 v253, s46, 24
	v_writelane_b32 v253, s47, 25
	v_writelane_b32 v253, s48, 26
	v_writelane_b32 v253, s49, 27
	v_writelane_b32 v253, s50, 28
	v_writelane_b32 v253, s51, 29
	v_writelane_b32 v253, s4, 30
	s_mov_b32 s36, 0xc000
	s_mov_b32 s39, 0x3e8293ee
	v_writelane_b32 v253, s5, 31
	s_add_u32 s4, s0, 0x2400
	v_writelane_b32 v253, s0, 32
	s_addc_u32 s5, s1, 0
	s_mov_b32 s38, 0x42000
	v_writelane_b32 v253, s1, 33
	v_writelane_b32 v253, s4, 34
	s_mov_b32 s37, 0x4ec4ec4f
	s_nop 0
	v_writelane_b32 v253, s5, 35
	s_load_dwordx8 s[4:11], s[20:21], 0x230
	s_waitcnt lgkmcnt(0)
	s_add_u32 s0, s4, 0x800
	v_writelane_b32 v253, s4, 36
	s_addc_u32 s1, s5, 0
	s_nop 0
	v_writelane_b32 v253, s5, 37
	v_writelane_b32 v253, s6, 38
	v_writelane_b32 v253, s7, 39
	v_writelane_b32 v253, s8, 40
	v_writelane_b32 v253, s9, 41
	v_writelane_b32 v253, s10, 42
	v_writelane_b32 v253, s11, 43
	s_load_dwordx16 s[4:19], s[20:21], 0x1f0
	v_writelane_b32 v253, s0, 44
	s_nop 1
	v_writelane_b32 v253, s1, 45
	s_waitcnt lgkmcnt(0)
	s_add_u32 s0, s16, 0x1000
	v_writelane_b32 v253, s4, 46
	s_addc_u32 s1, s17, 0
	s_nop 0
	v_writelane_b32 v253, s5, 47
	v_writelane_b32 v253, s6, 48
	v_writelane_b32 v253, s7, 49
	v_writelane_b32 v253, s8, 50
	v_writelane_b32 v253, s9, 51
	v_writelane_b32 v253, s10, 52
	v_writelane_b32 v253, s11, 53
	v_writelane_b32 v253, s12, 54
	v_writelane_b32 v253, s13, 55
	v_writelane_b32 v253, s14, 56
	v_writelane_b32 v253, s15, 57
	v_writelane_b32 v253, s16, 58
	v_writelane_b32 v253, s17, 59
	v_writelane_b32 v253, s18, 60
	v_writelane_b32 v253, s19, 61
	s_load_dwordx16 s[4:19], s[20:21], 0x1b0
	v_writelane_b32 v253, s0, 62
	s_nop 1
	v_writelane_b32 v253, s1, 63
	s_waitcnt lgkmcnt(0)
	s_add_u32 s0, s14, 0x200
	v_writelane_b32 v254, s4, 0
	s_addc_u32 s1, s15, 0
	s_nop 0
	v_writelane_b32 v254, s5, 1
	v_writelane_b32 v254, s6, 2
	v_writelane_b32 v254, s7, 3
	v_writelane_b32 v254, s8, 4
	v_writelane_b32 v254, s9, 5
	v_writelane_b32 v254, s10, 6
	v_writelane_b32 v254, s11, 7
	v_writelane_b32 v254, s12, 8
	v_writelane_b32 v254, s13, 9
	v_writelane_b32 v254, s14, 10
	v_writelane_b32 v254, s15, 11
	v_writelane_b32 v254, s16, 12
	v_writelane_b32 v254, s17, 13
	v_writelane_b32 v254, s18, 14
	v_writelane_b32 v254, s19, 15
	v_writelane_b32 v254, s0, 16
	s_load_dwordx4 s[4:7], s[20:21], 0x250
	s_nop 0
	v_writelane_b32 v254, s1, 17
	s_add_i32 s0, 16, 0x14000
	v_writelane_b32 v254, s0, 18
	v_readlane_b32 s0, v252, 8
	v_readlane_b32 s1, v252, 9
	s_mov_b32 s30, s0
	v_cmp_eq_u32_e64 s[0:1], 0, v0
	s_nop 1
	v_writelane_b32 v254, s0, 19
	s_nop 1
	v_writelane_b32 v254, s1, 20
	s_load_dwordx2 s[0:1], s[20:21], 0x260
	s_load_dwordx8 s[8:15], s[20:21], 0x0
	s_load_dwordx16 s[40:55], s[20:21], 0x30
	s_load_dwordx16 s[72:87], s[20:21], 0xf0
	s_waitcnt lgkmcnt(0)
	v_writelane_b32 v254, s0, 21
	s_nop 1
	v_writelane_b32 v254, s1, 22
	v_writelane_b32 v254, s4, 23
	s_nop 1
	v_writelane_b32 v254, s5, 24
	v_writelane_b32 v254, s6, 25
	v_writelane_b32 v254, s7, 26
	v_writelane_b32 v254, s40, 27
	s_nop 1
	v_writelane_b32 v254, s41, 28
	v_writelane_b32 v254, s42, 29
	v_writelane_b32 v254, s43, 30
	v_writelane_b32 v254, s44, 31
	v_writelane_b32 v254, s45, 32
	v_writelane_b32 v254, s46, 33
	v_writelane_b32 v254, s47, 34
	v_writelane_b32 v254, s48, 35
	v_writelane_b32 v254, s49, 36
	v_writelane_b32 v254, s50, 37
	v_writelane_b32 v254, s51, 38
	v_writelane_b32 v254, s52, 39
	v_writelane_b32 v254, s53, 40
	v_writelane_b32 v254, s54, 41
	v_writelane_b32 v254, s55, 42
	s_load_dwordx16 s[40:55], s[20:21], 0xb0
	s_waitcnt lgkmcnt(0)
	v_writelane_b32 v254, s40, 43
	s_nop 1
	v_writelane_b32 v254, s41, 44
	v_writelane_b32 v254, s42, 45
	v_writelane_b32 v254, s43, 46
	v_writelane_b32 v254, s44, 47
	v_writelane_b32 v254, s45, 48
	v_writelane_b32 v254, s46, 49
	v_writelane_b32 v254, s47, 50
	v_writelane_b32 v254, s48, 51
	v_writelane_b32 v254, s49, 52
	v_writelane_b32 v254, s50, 53
	v_writelane_b32 v254, s51, 54
	v_writelane_b32 v254, s52, 55
	v_writelane_b32 v254, s53, 56
	v_writelane_b32 v254, s54, 57
	v_writelane_b32 v254, s55, 58
	s_load_dwordx16 s[40:55], s[20:21], 0x70
	s_waitcnt lgkmcnt(0)
	v_writelane_b32 v254, s40, 59
	s_nop 1
	v_writelane_b32 v255, s45, 0
	v_writelane_b32 v255, s46, 1
	v_writelane_b32 v255, s47, 2
	v_writelane_b32 v255, s48, 3
	v_writelane_b32 v255, s49, 4
	v_writelane_b32 v255, s50, 5
	v_writelane_b32 v255, s51, 6
	v_writelane_b32 v255, s52, 7
	v_writelane_b32 v255, s53, 8
	v_writelane_b32 v255, s54, 9
	v_writelane_b32 v255, s55, 10
	v_writelane_b32 v255, s90, 11
	v_writelane_b32 v255, s8, 12
	v_writelane_b32 v254, s41, 60
	v_writelane_b32 v254, s42, 61
	v_writelane_b32 v255, s9, 13
	v_writelane_b32 v255, s10, 14
	v_writelane_b32 v255, s11, 15
	v_writelane_b32 v255, s12, 16
	v_writelane_b32 v255, s13, 17
	v_writelane_b32 v254, s43, 62
	v_writelane_b32 v255, s14, 18
	v_writelane_b32 v254, s44, 63
	v_writelane_b32 v255, s15, 19
	v_writelane_b32 v255, 0, 45
	s_branch .LBB0_11

.LBB0_396:
	v_readlane_b32 s0, v255, 45
	s_cmp_eq_u32 s0, 0
	s_cbranch_scc1 .LBB0_408
	v_mov_b32_e32 v2, v196
	s_sub_i32 s0, s2, 0xc0
	v_mov_b32_e32 v0, v196
	s_lshl_b32 s0, s0, 1
	v_readfirstlane_b32 s1, v0
	s_ashr_i32 s1, s1, 8
	v_mov_b32_e32 v0, v196
	s_add_i32 s1, s1, s0
	s_nop 0
	v_readfirstlane_b32 s0, v0
	s_ashr_i32 s0, s0, 8
	s_sub_i32 s20, s1, s0
	s_cmpk_gt_i32 s20, 0x23f
	s_cbranch_scc1 .LBB0_408
	v_mov_b32_e32 v0, 3
	v_lshlrev_b32_sdwa v4, v0, v2 dst_sel:DWORD dst_unused:UNUSED_PAD src0_sel:DWORD src1_sel:BYTE_0
	v_lshlrev_b32_e32 v0, 4, v2
	v_readlane_b32 s4, v253, 6
	s_waitcnt vmcnt(16)
	v_and_b32_e32 v9, 0x70, v0
	v_lshrrev_b32_e32 v0, 1, v2
	s_lshl_b32 s0, s55, 19
	v_readlane_b32 s6, v253, 8
	v_and_b32_e32 v3, 31, v2
	v_and_b32_e32 v0, 64, v0
	v_readlane_b32 s7, v253, 9
	s_add_u32 s21, s6, s0
	v_bfe_u32 v7, v2, 5, 1
	s_waitcnt vmcnt(1)
	v_or_b32_e32 v8, v0, v3
	s_addc_u32 s22, s7, 0
	s_mul_i32 s0, s55, 0x48000
	v_mul_u32_u24_e32 v8, 0x90, v8
	s_waitcnt vmcnt(15)
	v_lshlrev_b32_e32 v11, 4, v7
	s_add_u32 s23, s4, s0
	v_bfe_u32 v6, v2, 6, 2
	v_add3_u32 v66, s33, v8, v11
	v_mov_b32_e32 v8, s33
	s_movk_i32 s0, 0x4100
	v_mul_u32_u24_e32 v7, 0x104, v7
	s_waitcnt vmcnt(13)
	v_mad_u32_u24 v13, v6, s0, v8
	v_bfe_u32 v14, v2, 3, 5
	v_lshlrev_b32_e32 v7, 2, v7
	v_lshlrev_b32_e32 v3, 2, v3
	v_readlane_b32 s5, v253, 7
	v_and_b32_e32 v12, 0x5f, v2
	v_mul_u32_u24_e32 v14, 0x48, v14
	v_add3_u32 v69, v13, v7, v3
	v_mov_b32_e32 v3, s94
	s_movk_i32 s0, 0x90
	s_addc_u32 s24, s5, 0
	v_and_b32_e32 v5, 63, v2
	v_and_b32_e32 v67, 0x7f, v2
	v_or_b32_e32 v6, 0x800, v4
	v_or_b32_e32 v8, 0x1000, v4
	v_or_b32_e32 v10, 0x1800, v4
	v_lshlrev_b32_e32 v14, 1, v14
	v_mad_u32_u24 v3, v12, s0, v3
	s_add_i32 s0, 16, 0x4800
	v_lshrrev_b16_e32 v2, 1, v2
	v_add3_u32 v68, s33, v9, v14
	v_lshl_add_u32 v70, v5, 2, v13
	v_add3_u32 v71, v3, v11, s0
	v_and_b32_e32 v72, 64, v2
	v_lshlrev_b32_e32 v73, 1, v4
	v_lshlrev_b32_e32 v74, 1, v6
	v_lshlrev_b32_e32 v75, 1, v8
	v_lshlrev_b32_e32 v76, 1, v10
	s_branch .LBB0_399
.LBB0_398:
	s_movk_i32 s0, 0x40
	s_barrier
	s_lshl_b32 s0, s0, 1
	s_add_i32 s20, s0, s20
	s_cmpk_gt_i32 s20, 0x23f
	s_cbranch_scc1 .LBB0_408

.LBB0_408:
	v_readlane_b32 s0, v255, 45
	s_cmp_eq_u32 s0, 0
	s_cbranch_scc1 .Lfilt_skip
	v_writelane_b32 v255, 0, 45
	s_branch .Lw13_fret

.LBB0_949:
	s_bitcmp1_b32 s54, 0
	s_cbranch_scc1 .Lw13_nofilt
	s_cmp_lt_u32 s2, 0xc0
	s_cbranch_scc1 .Lw13_nofilt
	v_writelane_b32 v255, s4, 46
	v_writelane_b32 v255, s5, 47
	v_writelane_b32 v255, s6, 48
	v_writelane_b32 v255, s7, 49
	v_writelane_b32 v255, s20, 50
	v_writelane_b32 v255, s21, 51
	v_writelane_b32 v255, s22, 52
	v_writelane_b32 v255, s23, 53
	v_writelane_b32 v255, s24, 54
	v_writelane_b32 v255, s25, 55
	v_writelane_b32 v255, s26, 56
	v_writelane_b32 v255, s27, 57
	v_writelane_b32 v255, s28, 58
	v_writelane_b32 v255, s29, 59
	v_writelane_b32 v255, s40, 60
	v_writelane_b32 v255, s41, 61
	s_mov_b32 s0, 1
	s_nop 0
	v_writelane_b32 v255, s0, 45
	s_barrier
	s_branch .LBB0_396
.Lw13_fret:
	v_readlane_b32 s4, v255, 46
	v_readlane_b32 s5, v255, 47
	v_readlane_b32 s6, v255, 48
	v_readlane_b32 s7, v255, 49
	v_readlane_b32 s20, v255, 50
	v_readlane_b32 s21, v255, 51
	v_readlane_b32 s22, v255, 52
	v_readlane_b32 s23, v255, 53
	v_readlane_b32 s24, v255, 54
	v_readlane_b32 s25, v255, 55
	v_readlane_b32 s26, v255, 56
	v_readlane_b32 s27, v255, 57
	v_readlane_b32 s28, v255, 58
	v_readlane_b32 s29, v255, 59
	v_readlane_b32 s40, v255, 60
	v_readlane_b32 s41, v255, 61
